# adds: MLA block prologue requests all g_q_nope slices together with the q rows (one memory round trip instead of eight serialized)
# baseline (speedup 1.0000x reference)
.LBB0_145:
	s_xor_b64 s[30:31], s[18:19], -1
	s_and_b64 s[18:19], s[18:19], exec
	s_cselect_b32 s2, s84, s48
	s_cmp_lg_u64 s[30:31], 0
	s_cselect_b32 s100, 0xffffe000, s96
	s_cselect_b32 s101, -1, 0
	s_movk_i32 s8, 0xd0
	s_or_b32 s18, s34, s2
	s_ashr_i32 s19, s8, 31
	s_add_u32 s36, s0, s8
	s_addc_u32 s37, s1, s19
	s_load_dwordx2 s[36:37], s[36:37], 0x0
	s_mul_hi_u32 s19, s18, 0xa00
	s_mul_i32 s33, s35, 0xa00
	s_mul_i32 s8, s18, 0xa00
	s_add_i32 s19, s19, s33
	s_waitcnt lgkmcnt(0)
	s_add_u32 s8, s36, s8
	s_addc_u32 s19, s37, s19
	s_add_u32 s56, s8, s26
	s_movk_i32 s8, 0xd0
	s_addc_u32 s57, s19, s27
	s_ashr_i32 s19, s8, 31
	s_add_u32 s36, s0, s8
	s_addc_u32 s37, s1, s19
	s_load_dwordx2 s[42:43], s[36:37], 0x0
	v_lshl_add_u64 v[0:1], s[56:57], 0, v[170:171]
	v_lshl_add_u64 v[0:1], v[172:173], 1, v[0:1]
	s_mov_b64 s[56:57], 0x1a800000
	v_lshl_add_u64 v[24:25], v[0:1], 0, s[56:57]
	s_waitcnt lgkmcnt(0)
	s_add_u32 s8, s42, s9
	s_addc_u32 s19, s43, s49
	s_add_u32 s8, s8, s22
	s_addc_u32 s19, s19, s23
	s_add_u32 s36, s8, 0x32800000
	s_movk_i32 s8, 0xd0
	s_addc_u32 s37, s19, 0
	s_ashr_i32 s19, s8, 31
	s_add_u32 s74, s0, s8
	s_addc_u32 s75, s1, s19
	s_movk_i32 s8, 0xd0
	s_load_dwordx2 s[74:75], s[74:75], 0x0
	s_ashr_i32 s19, s8, 31
	s_add_u32 s76, s0, s8
	s_addc_u32 s77, s1, s19
	s_mov_b32 s19, 0x1a800000
	v_add_co_u32_e32 v2, vcc, s19, v0
	s_mov_b32 s8, 16
	s_nop 0
	v_addc_co_u32_e32 v3, vcc, 0, v1, vcc
	s_load_dwordx2 s[78:79], s[76:77], 0x0
	global_load_dwordx4 v[16:19], v[2:3], off
	global_load_dwordx4 v[20:23], v[24:25], off offset:32
	global_load_dwordx4 v[28:31], v[24:25], off offset:64
	global_load_dwordx4 v[32:35], v[24:25], off offset:96
	global_load_dwordx4 v[36:39], v[24:25], off offset:128
	global_load_dwordx4 v[4:7], v[24:25], off offset:352
	global_load_dwordx4 v[68:71], v[24:25], off offset:224
	global_load_dwordx4 v[12:15], v[24:25], off offset:256
	global_load_dwordx4 v[0:3], v[24:25], off offset:288
	global_load_dwordx4 v[8:11], v[24:25], off offset:320
	global_load_dwordx4 v[72:75], v[24:25], off offset:160
	global_load_dwordx4 v[76:79], v[24:25], off offset:192
	s_ashr_i32 s33, s8, 31
	s_add_u32 s76, s0, s8
	s_addc_u32 s77, s1, s33
	s_load_dwordx2 s[76:77], s[76:77], 0x0
	v_add_u32_e32 v26, s18, v167
	v_ashrrev_i32_e32 v27, 31, v26
	global_load_dwordx4 v[80:83], v[174:175], off offset:16
	global_load_dwordx4 v[84:87], v[174:175], off
	global_load_dwordx4 v[110:113], v[174:175], off offset:80
	global_load_dwordx4 v[114:117], v[174:175], off offset:64
	global_load_dwordx4 v[118:121], v[174:175], off offset:144
	global_load_dwordx4 v[122:125], v[174:175], off offset:128
	global_load_dwordx4 v[126:129], v[174:175], off offset:208
	global_load_dwordx4 v[206:209], v[174:175], off offset:192
	global_load_dwordx4 v[156:159], v[174:175], off offset:272
	global_load_dwordx4 v[160:163], v[174:175], off offset:256
	global_load_dwordx4 v[148:151], v[174:175], off offset:336
	global_load_dwordx4 v[152:155], v[174:175], off offset:320
	global_load_dwordx4 v[138:141], v[174:175], off offset:400
	global_load_dwordx4 v[142:145], v[174:175], off offset:384
	global_load_dwordx4 v[130:133], v[174:175], off offset:448
	global_load_dwordx4 v[134:137], v[174:175], off offset:464
	s_waitcnt lgkmcnt(0)
	s_add_u32 s8, s74, s20
	v_lshl_add_u64 v[24:25], v[26:27], 2, s[76:77]
	global_load_dword v27, v[24:25], off
	s_addc_u32 s33, s75, s21
	s_mov_b32 s19, s35
	s_mov_b32 s57, 2
	s_add_u32 vcc_lo, s8, 0x3e800000
	s_mov_b32 s8, 0
	s_addc_u32 vcc_hi, s33, 0
	s_waitcnt vmcnt(22)
	v_lshlrev_b32_e32 v24, 16, v68
	v_lshlrev_b32_e32 v102, 16, v20
	v_and_b32_e32 v104, 0xffff0000, v20
	v_and_b32_e32 v90, 0xffff0000, v16
	v_lshlrev_b32_e32 v88, 16, v16
	v_lshlrev_b32_e32 v89, 16, v17
	v_and_b32_e32 v91, 0xffff0000, v17
	v_mul_f32_e32 v17, v90, v90
	v_fmac_f32_e32 v17, v88, v88
	v_fmac_f32_e32 v17, v89, v89
	v_lshlrev_b32_e32 v92, 16, v18
	v_fmac_f32_e32 v17, v91, v91
	v_and_b32_e32 v94, 0xffff0000, v18
	v_fmac_f32_e32 v17, v92, v92
	v_lshlrev_b32_e32 v93, 16, v19
	v_fmac_f32_e32 v17, v94, v94
	v_and_b32_e32 v95, 0xffff0000, v19
	v_fmac_f32_e32 v17, v93, v93
	v_fmac_f32_e32 v17, v95, v95
	v_fmac_f32_e32 v17, v102, v102
	v_lshlrev_b32_e32 v103, 16, v21
	v_fmac_f32_e32 v17, v104, v104
	v_and_b32_e32 v105, 0xffff0000, v21
	v_fmac_f32_e32 v17, v103, v103
	v_lshlrev_b32_e32 v106, 16, v22
	v_fmac_f32_e32 v17, v105, v105
	v_and_b32_e32 v108, 0xffff0000, v22
	v_fmac_f32_e32 v17, v106, v106
	v_lshlrev_b32_e32 v107, 16, v23
	v_fmac_f32_e32 v17, v108, v108
	v_and_b32_e32 v109, 0xffff0000, v23
	v_fmac_f32_e32 v17, v107, v107
	v_lshlrev_b32_e32 v66, 16, v28
	v_fmac_f32_e32 v17, v109, v109
	v_and_b32_e32 v64, 0xffff0000, v28
	v_fmac_f32_e32 v17, v66, v66
	v_lshlrev_b32_e32 v67, 16, v29
	v_fmac_f32_e32 v17, v64, v64
	v_and_b32_e32 v65, 0xffff0000, v29
	v_fmac_f32_e32 v17, v67, v67
	v_lshlrev_b32_e32 v62, 16, v30
	v_fmac_f32_e32 v17, v65, v65
	v_and_b32_e32 v60, 0xffff0000, v30
	v_fmac_f32_e32 v17, v62, v62
	v_lshlrev_b32_e32 v63, 16, v31
	v_fmac_f32_e32 v17, v60, v60
	v_and_b32_e32 v61, 0xffff0000, v31
	v_fmac_f32_e32 v17, v63, v63
	v_lshlrev_b32_e32 v58, 16, v32
	v_fmac_f32_e32 v17, v61, v61
	v_and_b32_e32 v56, 0xffff0000, v32
	v_fmac_f32_e32 v17, v58, v58
	v_lshlrev_b32_e32 v59, 16, v33
	v_fmac_f32_e32 v17, v56, v56
	v_and_b32_e32 v57, 0xffff0000, v33
	v_fmac_f32_e32 v17, v59, v59
	v_lshlrev_b32_e32 v54, 16, v34
	v_fmac_f32_e32 v17, v57, v57
	v_and_b32_e32 v52, 0xffff0000, v34
	v_fmac_f32_e32 v17, v54, v54
	v_lshlrev_b32_e32 v55, 16, v35
	v_fmac_f32_e32 v17, v52, v52
	v_and_b32_e32 v53, 0xffff0000, v35
	v_fmac_f32_e32 v17, v55, v55
	v_lshlrev_b32_e32 v50, 16, v36
	v_fmac_f32_e32 v17, v53, v53
	v_and_b32_e32 v48, 0xffff0000, v36
	v_fmac_f32_e32 v17, v50, v50
	v_lshlrev_b32_e32 v51, 16, v37
	v_fmac_f32_e32 v17, v48, v48
	v_and_b32_e32 v49, 0xffff0000, v37
	v_fmac_f32_e32 v17, v51, v51
	v_lshlrev_b32_e32 v46, 16, v38
	v_fmac_f32_e32 v17, v49, v49
	v_and_b32_e32 v44, 0xffff0000, v38
	v_fmac_f32_e32 v17, v46, v46
	v_fmac_f32_e32 v17, v44, v44
	v_lshlrev_b32_e32 v47, 16, v39
	v_fmac_f32_e32 v17, v47, v47
	v_and_b32_e32 v45, 0xffff0000, v39
	v_fmac_f32_e32 v17, v45, v45
	s_waitcnt vmcnt(18)
	v_lshlrev_b32_e32 v42, 16, v72
	v_fmac_f32_e32 v17, v42, v42
	v_and_b32_e32 v40, 0xffff0000, v72
	v_fmac_f32_e32 v17, v40, v40
	v_lshlrev_b32_e32 v43, 16, v73
	v_fmac_f32_e32 v17, v43, v43
	v_and_b32_e32 v41, 0xffff0000, v73
	v_fmac_f32_e32 v17, v41, v41
	v_lshlrev_b32_e32 v38, 16, v74
	v_fmac_f32_e32 v17, v38, v38
	v_and_b32_e32 v36, 0xffff0000, v74
	v_fmac_f32_e32 v17, v36, v36
	v_lshlrev_b32_e32 v39, 16, v75
	v_fmac_f32_e32 v17, v39, v39
	v_and_b32_e32 v37, 0xffff0000, v75
	v_fmac_f32_e32 v17, v37, v37
	s_waitcnt vmcnt(17)
	v_lshlrev_b32_e32 v34, 16, v76
	v_fmac_f32_e32 v17, v34, v34
	v_and_b32_e32 v32, 0xffff0000, v76
	v_fmac_f32_e32 v17, v32, v32
	v_lshlrev_b32_e32 v35, 16, v77
	v_fmac_f32_e32 v17, v35, v35
	v_and_b32_e32 v33, 0xffff0000, v77
	v_fmac_f32_e32 v17, v33, v33
	v_lshlrev_b32_e32 v30, 16, v78
	v_fmac_f32_e32 v17, v30, v30
	v_and_b32_e32 v28, 0xffff0000, v78
	v_fmac_f32_e32 v17, v28, v28
	v_lshlrev_b32_e32 v31, 16, v79
	v_fmac_f32_e32 v17, v31, v31
	v_and_b32_e32 v29, 0xffff0000, v79
	v_fmac_f32_e32 v17, v29, v29
	v_fmac_f32_e32 v17, v24, v24
	v_and_b32_e32 v22, 0xffff0000, v68
	v_fmac_f32_e32 v17, v22, v22
	v_lshlrev_b32_e32 v25, 16, v69
	v_fmac_f32_e32 v17, v25, v25
	v_and_b32_e32 v23, 0xffff0000, v69
	v_fmac_f32_e32 v17, v23, v23
	v_lshlrev_b32_e32 v16, 16, v70
	v_fmac_f32_e32 v17, v16, v16
	v_and_b32_e32 v18, 0xffff0000, v70
	v_and_b32_e32 v21, 0xffff0000, v71
	v_lshlrev_b32_e32 v20, 16, v71
	v_fmac_f32_e32 v17, v18, v18
	v_pk_mul_f32 v[68:69], v[20:21], v[20:21]
	s_waitcnt vmcnt(15)
	v_mov_b32_e32 v70, v84
	v_add_f32_e32 v17, v17, v68
	v_add_f32_e32 v17, v17, v69
	v_mov_b32_e32 v19, v17
	s_nop 1
	v_permlane32_swap_b32_e32 v17, v19
	v_add_f32_e32 v17, v17, v19
	v_fmamk_f32 v17, v17, 0x3c000000, v253
	v_rsq_f32_e32 v17, v17
	v_mov_b32_e32 v71, v86
	v_mov_b32_e32 v74, v80
	v_mov_b32_e32 v75, v82
	v_mul_f32_e32 v26, 0x3d93cd3a, v17
	s_waitcnt vmcnt(0)
	v_pk_mul_f32 v[68:69], v[26:27], v[88:89] op_sel_hi:[0,1]
	v_pk_mul_f32 v[72:73], v[26:27], v[92:93] op_sel_hi:[0,1]
	v_pk_mul_f32 v[68:69], v[70:71], v[68:69]
	v_pk_mul_f32 v[70:71], v[26:27], v[90:91] op_sel_hi:[0,1]
	v_mov_b32_e32 v86, v85
	v_pk_mul_f32 v[72:73], v[74:75], v[72:73]
	v_pk_mul_f32 v[74:75], v[26:27], v[94:95] op_sel_hi:[0,1]
	v_mov_b32_e32 v82, v81
	v_pk_mul_f32 v[70:71], v[86:87], v[70:71]
	v_pk_mul_f32 v[74:75], v[82:83], v[74:75]
	v_bfe_u32 v76, v71, 16, 1
	v_bfe_u32 v17, v75, 16, 1
	v_bfe_u32 v19, v74, 16, 1
	v_bfe_u32 v77, v70, 16, 1
	v_add3_u32 v70, v70, v77, s64
	v_add3_u32 v71, v71, v76, s64
	v_add3_u32 v19, v74, v19, s64
	v_add3_u32 v17, v75, v17, s64
	v_bfe_u32 v74, v68, 16, 1
	v_bfe_u32 v75, v69, 16, 1
	v_bfe_u32 v76, v72, 16, 1
	v_bfe_u32 v77, v73, 16, 1
	v_add3_u32 v73, v73, v77, s64
	v_add3_u32 v72, v72, v76, s64
	v_add3_u32 v69, v69, v75, s64
	v_add3_u32 v68, v68, v74, s64
	v_lshrrev_b32_e32 v68, 16, v68
	v_lshrrev_b32_e32 v69, 16, v69
	v_lshrrev_b32_e32 v72, 16, v72
	v_lshrrev_b32_e32 v73, 16, v73
	v_and_or_b32 v101, v17, s3, v73
	v_and_or_b32 v100, v19, s3, v72
	v_and_or_b32 v99, v71, s3, v69
	v_and_or_b32 v98, v70, s3, v68
	v_mov_b32_e32 v68, v110
	v_mov_b32_e32 v69, v111
	v_mov_b32_e32 v70, v112
	v_mov_b32_e32 v71, v113
	v_mov_b32_e32 v72, v114
	v_mov_b32_e32 v73, v115
	v_mov_b32_e32 v74, v116
	v_mov_b32_e32 v75, v117
	v_pk_mul_f32 v[76:77], v[26:27], v[102:103] op_sel_hi:[0,1]
	s_waitcnt vmcnt(0)
	v_mov_b32_e32 v78, v72
	v_mov_b32_e32 v79, v74
	v_pk_mul_f32 v[76:77], v[78:79], v[76:77]
	v_pk_mul_f32 v[78:79], v[26:27], v[104:105] op_sel_hi:[0,1]
	v_mov_b32_e32 v74, v73
	v_pk_mul_f32 v[72:73], v[74:75], v[78:79]
	v_pk_mul_f32 v[74:75], v[26:27], v[106:107] op_sel_hi:[0,1]
	v_mov_b32_e32 v78, v68
	v_mov_b32_e32 v79, v70
	v_pk_mul_f32 v[74:75], v[78:79], v[74:75]
	v_pk_mul_f32 v[78:79], v[26:27], v[108:109] op_sel_hi:[0,1]
	v_mov_b32_e32 v70, v69
	v_pk_mul_f32 v[68:69], v[70:71], v[78:79]
	v_bfe_u32 v70, v73, 16, 1
	v_bfe_u32 v17, v69, 16, 1
	v_bfe_u32 v19, v68, 16, 1
	v_bfe_u32 v71, v72, 16, 1
	v_add3_u32 v71, v72, v71, s64
	v_add3_u32 v70, v73, v70, s64
	v_add3_u32 v19, v68, v19, s64
	v_add3_u32 v17, v69, v17, s64
	v_bfe_u32 v68, v76, 16, 1
	v_bfe_u32 v69, v77, 16, 1
	v_bfe_u32 v72, v74, 16, 1
	v_bfe_u32 v73, v75, 16, 1
	v_add3_u32 v73, v75, v73, s64
	v_add3_u32 v72, v74, v72, s64
	v_add3_u32 v69, v77, v69, s64
	v_add3_u32 v68, v76, v68, s64
	v_lshrrev_b32_e32 v68, 16, v68
	v_lshrrev_b32_e32 v69, 16, v69
	v_lshrrev_b32_e32 v72, 16, v72
	v_lshrrev_b32_e32 v73, 16, v73
	v_and_or_b32 v105, v17, s3, v73
	v_and_or_b32 v104, v19, s3, v72
	v_and_or_b32 v103, v70, s3, v69
	v_and_or_b32 v102, v71, s3, v68
	v_mov_b32_e32 v68, v118
	v_mov_b32_e32 v69, v119
	v_mov_b32_e32 v70, v120
	v_mov_b32_e32 v71, v121
	v_mov_b32_e32 v72, v122
	v_mov_b32_e32 v73, v123
	v_mov_b32_e32 v74, v124
	v_mov_b32_e32 v75, v125
	v_pk_mul_f32 v[64:65], v[26:27], v[64:65] op_sel_hi:[0,1]
	v_pk_mul_f32 v[60:61], v[26:27], v[60:61] op_sel_hi:[0,1]
	v_pk_mul_f32 v[66:67], v[26:27], v[66:67] op_sel_hi:[0,1]
	v_pk_mul_f32 v[62:63], v[26:27], v[62:63] op_sel_hi:[0,1]
	s_waitcnt vmcnt(0)
	v_mov_b32_e32 v77, v74
	v_mov_b32_e32 v74, v73
	v_mov_b32_e32 v73, v70
	v_mov_b32_e32 v70, v69
	v_mov_b32_e32 v76, v72
	v_pk_mul_f32 v[64:65], v[74:75], v[64:65]
	v_mov_b32_e32 v72, v68
	v_pk_mul_f32 v[60:61], v[70:71], v[60:61]
	v_pk_mul_f32 v[66:67], v[76:77], v[66:67]
	v_pk_mul_f32 v[62:63], v[72:73], v[62:63]
	v_bfe_u32 v17, v61, 16, 1
	v_bfe_u32 v19, v60, 16, 1
	v_bfe_u32 v68, v65, 16, 1
	v_bfe_u32 v69, v64, 16, 1
	v_add3_u32 v64, v64, v69, s64
	v_add3_u32 v65, v65, v68, s64
	v_add3_u32 v19, v60, v19, s64
	v_add3_u32 v17, v61, v17, s64
	v_bfe_u32 v60, v66, 16, 1
	v_bfe_u32 v61, v67, 16, 1
	v_bfe_u32 v68, v62, 16, 1
	v_bfe_u32 v69, v63, 16, 1
	v_add3_u32 v63, v63, v69, s64
	v_add3_u32 v62, v62, v68, s64
	v_add3_u32 v61, v67, v61, s64
	v_add3_u32 v60, v66, v60, s64
	v_lshrrev_b32_e32 v60, 16, v60
	v_lshrrev_b32_e32 v61, 16, v61
	v_lshrrev_b32_e32 v62, 16, v62
	v_lshrrev_b32_e32 v63, 16, v63
	v_and_or_b32 v109, v17, s3, v63
	v_and_or_b32 v108, v19, s3, v62
	v_and_or_b32 v107, v65, s3, v61
	v_and_or_b32 v106, v64, s3, v60
	v_mov_b32_e32 v60, v126
	v_mov_b32_e32 v61, v127
	v_mov_b32_e32 v62, v128
	v_mov_b32_e32 v63, v129
	v_mov_b32_e32 v64, v206
	v_mov_b32_e32 v65, v207
	v_mov_b32_e32 v66, v208
	v_mov_b32_e32 v67, v209
	v_pk_mul_f32 v[56:57], v[26:27], v[56:57] op_sel_hi:[0,1]
	v_pk_mul_f32 v[52:53], v[26:27], v[52:53] op_sel_hi:[0,1]
	v_pk_mul_f32 v[58:59], v[26:27], v[58:59] op_sel_hi:[0,1]
	v_pk_mul_f32 v[54:55], v[26:27], v[54:55] op_sel_hi:[0,1]
	s_waitcnt vmcnt(0)
	v_mov_b32_e32 v69, v66
	v_mov_b32_e32 v66, v65
	v_mov_b32_e32 v65, v62
	v_mov_b32_e32 v62, v61
	v_mov_b32_e32 v68, v64
	v_pk_mul_f32 v[56:57], v[66:67], v[56:57]
	v_mov_b32_e32 v64, v60
	v_pk_mul_f32 v[52:53], v[62:63], v[52:53]
	v_pk_mul_f32 v[58:59], v[68:69], v[58:59]
	v_pk_mul_f32 v[54:55], v[64:65], v[54:55]
	v_bfe_u32 v17, v53, 16, 1
	v_bfe_u32 v19, v52, 16, 1
	v_bfe_u32 v60, v57, 16, 1
	v_bfe_u32 v61, v56, 16, 1
	v_add3_u32 v56, v56, v61, s64
	v_add3_u32 v57, v57, v60, s64
	v_add3_u32 v19, v52, v19, s64
	v_add3_u32 v17, v53, v17, s64
	v_bfe_u32 v52, v58, 16, 1
	v_bfe_u32 v53, v59, 16, 1
	v_bfe_u32 v60, v54, 16, 1
	v_bfe_u32 v61, v55, 16, 1
	v_add3_u32 v55, v55, v61, s64
	v_add3_u32 v54, v54, v60, s64
	v_add3_u32 v53, v59, v53, s64
	v_add3_u32 v52, v58, v52, s64
	v_lshrrev_b32_e32 v52, 16, v52
	v_lshrrev_b32_e32 v53, 16, v53
	v_lshrrev_b32_e32 v54, 16, v54
	v_lshrrev_b32_e32 v55, 16, v55
	v_and_or_b32 v113, v17, s3, v55
	v_and_or_b32 v112, v19, s3, v54
	v_and_or_b32 v111, v57, s3, v53
	v_and_or_b32 v110, v56, s3, v52
	v_mov_b32_e32 v52, v156
	v_mov_b32_e32 v53, v157
	v_mov_b32_e32 v54, v158
	v_mov_b32_e32 v55, v159
	v_mov_b32_e32 v56, v160
	v_mov_b32_e32 v57, v161
	v_mov_b32_e32 v58, v162
	v_mov_b32_e32 v59, v163
	v_pk_mul_f32 v[48:49], v[26:27], v[48:49] op_sel_hi:[0,1]
	v_pk_mul_f32 v[44:45], v[26:27], v[44:45] op_sel_hi:[0,1]
	v_pk_mul_f32 v[50:51], v[26:27], v[50:51] op_sel_hi:[0,1]
	v_pk_mul_f32 v[46:47], v[26:27], v[46:47] op_sel_hi:[0,1]
	s_waitcnt vmcnt(0)
	v_mov_b32_e32 v61, v58
	v_mov_b32_e32 v58, v57
	v_mov_b32_e32 v57, v54
	v_mov_b32_e32 v54, v53
	v_mov_b32_e32 v60, v56
	v_pk_mul_f32 v[48:49], v[58:59], v[48:49]
	v_mov_b32_e32 v56, v52
	v_pk_mul_f32 v[44:45], v[54:55], v[44:45]
	v_pk_mul_f32 v[50:51], v[60:61], v[50:51]
	v_pk_mul_f32 v[46:47], v[56:57], v[46:47]
	v_bfe_u32 v17, v45, 16, 1
	v_bfe_u32 v19, v44, 16, 1
	v_bfe_u32 v52, v49, 16, 1
	v_bfe_u32 v53, v48, 16, 1
	v_add3_u32 v48, v48, v53, s64
	v_add3_u32 v49, v49, v52, s64
	v_add3_u32 v19, v44, v19, s64
	v_add3_u32 v17, v45, v17, s64
	v_bfe_u32 v44, v50, 16, 1
	v_bfe_u32 v45, v51, 16, 1
	v_bfe_u32 v52, v46, 16, 1
	v_bfe_u32 v53, v47, 16, 1
	v_add3_u32 v47, v47, v53, s64
	v_add3_u32 v46, v46, v52, s64
	v_add3_u32 v45, v51, v45, s64
	v_add3_u32 v44, v50, v44, s64
	v_lshrrev_b32_e32 v44, 16, v44
	v_lshrrev_b32_e32 v45, 16, v45
	v_lshrrev_b32_e32 v46, 16, v46
	v_lshrrev_b32_e32 v47, 16, v47
	v_and_or_b32 v117, v17, s3, v47
	v_and_or_b32 v116, v19, s3, v46
	v_and_or_b32 v115, v49, s3, v45
	v_and_or_b32 v114, v48, s3, v44
	v_mov_b32_e32 v44, v148
	v_mov_b32_e32 v45, v149
	v_mov_b32_e32 v46, v150
	v_mov_b32_e32 v47, v151
	v_mov_b32_e32 v48, v152
	v_mov_b32_e32 v49, v153
	v_mov_b32_e32 v50, v154
	v_mov_b32_e32 v51, v155
	v_pk_mul_f32 v[40:41], v[26:27], v[40:41] op_sel_hi:[0,1]
	v_pk_mul_f32 v[36:37], v[26:27], v[36:37] op_sel_hi:[0,1]
	v_pk_mul_f32 v[42:43], v[26:27], v[42:43] op_sel_hi:[0,1]
	v_pk_mul_f32 v[38:39], v[26:27], v[38:39] op_sel_hi:[0,1]
	s_waitcnt vmcnt(0)
	v_mov_b32_e32 v53, v50
	v_mov_b32_e32 v50, v49
	v_mov_b32_e32 v49, v46
	v_mov_b32_e32 v46, v45
	v_mov_b32_e32 v52, v48
	v_pk_mul_f32 v[40:41], v[50:51], v[40:41]
	v_mov_b32_e32 v48, v44
	v_pk_mul_f32 v[36:37], v[46:47], v[36:37]
	v_pk_mul_f32 v[42:43], v[52:53], v[42:43]
	v_pk_mul_f32 v[38:39], v[48:49], v[38:39]
	v_bfe_u32 v17, v37, 16, 1
	v_bfe_u32 v19, v36, 16, 1
	v_bfe_u32 v44, v41, 16, 1
	v_bfe_u32 v45, v40, 16, 1
	v_add3_u32 v40, v40, v45, s64
	v_add3_u32 v41, v41, v44, s64
	v_add3_u32 v19, v36, v19, s64
	v_add3_u32 v17, v37, v17, s64
	v_bfe_u32 v36, v42, 16, 1
	v_bfe_u32 v37, v43, 16, 1
	v_bfe_u32 v44, v38, 16, 1
	v_bfe_u32 v45, v39, 16, 1
	v_add3_u32 v39, v39, v45, s64
	v_add3_u32 v38, v38, v44, s64
	v_add3_u32 v37, v43, v37, s64
	v_add3_u32 v36, v42, v36, s64
	v_lshrrev_b32_e32 v36, 16, v36
	v_lshrrev_b32_e32 v37, 16, v37
	v_lshrrev_b32_e32 v38, 16, v38
	v_lshrrev_b32_e32 v39, 16, v39
	v_and_or_b32 v121, v17, s3, v39
	v_and_or_b32 v120, v19, s3, v38
	v_and_or_b32 v119, v41, s3, v37
	v_and_or_b32 v118, v40, s3, v36
	v_mov_b32_e32 v36, v138
	v_mov_b32_e32 v37, v139
	v_mov_b32_e32 v38, v140
	v_mov_b32_e32 v39, v141
	v_mov_b32_e32 v40, v142
	v_mov_b32_e32 v41, v143
	v_mov_b32_e32 v42, v144
	v_mov_b32_e32 v43, v145
	v_pk_mul_f32 v[32:33], v[26:27], v[32:33] op_sel_hi:[0,1]
	v_pk_mul_f32 v[28:29], v[26:27], v[28:29] op_sel_hi:[0,1]
	v_pk_mul_f32 v[34:35], v[26:27], v[34:35] op_sel_hi:[0,1]
	v_pk_mul_f32 v[30:31], v[26:27], v[30:31] op_sel_hi:[0,1]
	s_waitcnt vmcnt(0)
	v_mov_b32_e32 v45, v42
	v_mov_b32_e32 v42, v41
	v_mov_b32_e32 v41, v38
	v_mov_b32_e32 v38, v37
	v_mov_b32_e32 v44, v40
	v_pk_mul_f32 v[32:33], v[42:43], v[32:33]
	v_mov_b32_e32 v40, v36
	v_pk_mul_f32 v[28:29], v[38:39], v[28:29]
	v_pk_mul_f32 v[34:35], v[44:45], v[34:35]
	v_pk_mul_f32 v[30:31], v[40:41], v[30:31]
	v_bfe_u32 v17, v29, 16, 1
	v_bfe_u32 v19, v28, 16, 1
	v_bfe_u32 v36, v33, 16, 1
	v_bfe_u32 v37, v32, 16, 1
	v_add3_u32 v32, v32, v37, s64
	v_add3_u32 v33, v33, v36, s64
	v_add3_u32 v19, v28, v19, s64
	v_add3_u32 v17, v29, v17, s64
	v_bfe_u32 v28, v34, 16, 1
	v_bfe_u32 v29, v35, 16, 1
	v_bfe_u32 v36, v30, 16, 1
	v_bfe_u32 v37, v31, 16, 1
	v_add3_u32 v31, v31, v37, s64
	v_add3_u32 v30, v30, v36, s64
	v_add3_u32 v29, v35, v29, s64
	v_add3_u32 v28, v34, v28, s64
	v_lshrrev_b32_e32 v28, 16, v28
	v_lshrrev_b32_e32 v29, 16, v29
	v_lshrrev_b32_e32 v30, 16, v30
	v_lshrrev_b32_e32 v31, 16, v31
	v_and_or_b32 v125, v17, s3, v31
	v_and_or_b32 v124, v19, s3, v30
	v_and_or_b32 v123, v33, s3, v29
	v_and_or_b32 v122, v32, s3, v28
	v_mov_b32_e32 v28, v130
	v_mov_b32_e32 v29, v131
	v_mov_b32_e32 v30, v132
	v_mov_b32_e32 v31, v133
	v_mov_b32_e32 v32, v134
	v_mov_b32_e32 v33, v135
	v_mov_b32_e32 v34, v136
	v_mov_b32_e32 v35, v137
	v_mov_b32_e32 v17, v20
	v_pk_mul_f32 v[24:25], v[26:27], v[24:25] op_sel_hi:[0,1]
	v_mov_b32_e32 v19, v21
	v_pk_mul_f32 v[16:17], v[26:27], v[16:17] op_sel_hi:[0,1]
	v_pk_mul_f32 v[22:23], v[26:27], v[22:23] op_sel_hi:[0,1]
	v_pk_mul_f32 v[18:19], v[26:27], v[18:19] op_sel_hi:[0,1]
	s_waitcnt vmcnt(1)
	v_mov_b32_e32 v20, v28
	v_mov_b32_e32 v21, v30
	v_mov_b32_e32 v30, v29
	s_waitcnt vmcnt(0)
	v_mov_b32_e32 v28, v32
	v_mov_b32_e32 v29, v34
	v_mov_b32_e32 v34, v33
	v_pk_mul_f32 v[20:21], v[20:21], v[24:25]
	v_pk_mul_f32 v[16:17], v[28:29], v[16:17]
	v_pk_mul_f32 v[22:23], v[30:31], v[22:23]
	v_pk_mul_f32 v[18:19], v[34:35], v[18:19]
	v_bfe_u32 v29, v20, 16, 1
	v_bfe_u32 v30, v21, 16, 1
	v_bfe_u32 v31, v16, 16, 1
	v_bfe_u32 v32, v17, 16, 1
	v_bfe_u32 v24, v19, 16, 1
	v_bfe_u32 v25, v18, 16, 1
	v_bfe_u32 v26, v23, 16, 1
	v_bfe_u32 v28, v22, 16, 1
	v_add3_u32 v17, v17, v32, s64
	v_add3_u32 v16, v16, v31, s64
	v_add3_u32 v21, v21, v30, s64
	v_add3_u32 v20, v20, v29, s64
	v_add3_u32 v22, v22, v28, s64
	v_add3_u32 v23, v23, v26, s64
	v_add3_u32 v18, v18, v25, s64
	v_add3_u32 v19, v19, v24, s64
	v_lshrrev_b32_e32 v20, 16, v20
	v_lshrrev_b32_e32 v21, 16, v21
	v_lshrrev_b32_e32 v16, 16, v16
	v_lshrrev_b32_e32 v17, 16, v17
	v_and_or_b32 v129, v19, s3, v17
	v_and_or_b32 v128, v18, s3, v16
	v_and_or_b32 v127, v23, s3, v21
	v_and_or_b32 v126, v22, s3, v20
	global_load_dwordx4 v[30:33], v[192:193], off
	global_load_dwordx3 v[16:18], v[192:193], off offset:16
	global_load_dword v42, v[190:191], off
	global_load_dword v40, v[190:191], off offset:128
	v_cvt_f32_i32_e32 v146, v27
	v_lshlrev_b32_e32 v24, 16, v6
	v_and_b32_e32 v20, 0xffff0000, v6
	v_and_b32_e32 v23, 0xffff0000, v7
	v_lshlrev_b32_e32 v22, 16, v7
	v_lshlrev_b32_e32 v47, 16, v13
	v_lshlrev_b32_e32 v46, 16, v12
	v_and_b32_e32 v45, 0xffff0000, v13
	v_and_b32_e32 v44, 0xffff0000, v12
	v_lshlrev_b32_e32 v49, 16, v9
	v_lshlrev_b32_e32 v48, 16, v8
	v_and_b32_e32 v51, 0xffff0000, v9
	v_and_b32_e32 v50, 0xffff0000, v8
	v_pk_mul_f32 v[56:57], v[22:23], v[22:23]
	v_pk_mul_f32 v[62:63], v[46:47], v[46:47]
	v_pk_mul_f32 v[64:65], v[44:45], v[44:45]
	v_pk_mul_f32 v[58:59], v[48:49], v[48:49]
	v_pk_mul_f32 v[60:61], v[50:51], v[50:51]
	s_waitcnt vmcnt(3)
	v_mul_f32_e32 v6, v30, v146
	v_cvt_f64_f32_e32 v[6:7], v6
	v_mul_f64 v[12:13], v[6:7], s[82:83]
	v_rndne_f64_e32 v[12:13], v[12:13]
	v_fma_f64 v[6:7], v[6:7], s[82:83], -v[12:13]
	v_cvt_f32_f64_e32 v6, v[6:7]
	v_cos_f32_e32 v12, v6
	v_sin_f32_e32 v26, v6
	global_load_dword v54, v[190:191], off offset:4
	global_load_dword v52, v[190:191], off offset:132
	global_load_dword v43, v[190:191], off offset:8
	global_load_dword v41, v[190:191], off offset:136
	v_mul_f32_e32 v6, v31, v146
	v_cvt_f64_f32_e32 v[6:7], v6
	v_mul_f64 v[8:9], v[6:7], s[82:83]
	v_rndne_f64_e32 v[8:9], v[8:9]
	v_fma_f64 v[6:7], v[6:7], s[82:83], -v[8:9]
	v_cvt_f32_f64_e32 v6, v[6:7]
	v_cos_f32_e32 v28, v6
	v_sin_f32_e32 v30, v6
	global_load_dword v55, v[190:191], off offset:12
	global_load_dword v53, v[190:191], off offset:140
	v_mul_f32_e32 v6, v32, v146
	v_cvt_f64_f32_e32 v[6:7], v6
	v_mul_f64 v[8:9], v[6:7], s[82:83]
	v_rndne_f64_e32 v[8:9], v[8:9]
	v_fma_f64 v[6:7], v[6:7], s[82:83], -v[8:9]
	v_cvt_f32_f64_e32 v6, v[6:7]
	v_cos_f32_e32 v13, v6
	v_sin_f32_e32 v27, v6
	v_mul_f32_e32 v6, v33, v146
	v_cvt_f64_f32_e32 v[6:7], v6
	v_mul_f64 v[8:9], v[6:7], s[82:83]
	v_rndne_f64_e32 v[8:9], v[8:9]
	v_fma_f64 v[6:7], v[6:7], s[82:83], -v[8:9]
	v_cvt_f32_f64_e32 v6, v[6:7]
	v_cos_f32_e32 v29, v6
	v_sin_f32_e32 v31, v6
	global_load_dword v70, v[190:191], off offset:16
	global_load_dword v68, v[190:191], off offset:144
	s_waitcnt vmcnt(10)
	v_mul_f32_e32 v6, v16, v146
	v_cvt_f64_f32_e32 v[6:7], v6
	v_mul_f64 v[8:9], v[6:7], s[82:83]
	v_rndne_f64_e32 v[8:9], v[8:9]
	v_fma_f64 v[6:7], v[6:7], s[82:83], -v[8:9]
	v_cvt_f32_f64_e32 v6, v[6:7]
	v_cos_f32_e32 v16, v6
	v_sin_f32_e32 v32, v6
	v_lshlrev_b32_e32 v67, 16, v15
	v_lshlrev_b32_e32 v66, 16, v14
	v_and_b32_e32 v35, 0xffff0000, v15
	v_and_b32_e32 v34, 0xffff0000, v14
	v_lshlrev_b32_e32 v39, 16, v11
	v_lshlrev_b32_e32 v38, 16, v10
	v_and_b32_e32 v37, 0xffff0000, v11
	v_and_b32_e32 v36, 0xffff0000, v10
	v_pk_mul_f32 v[76:77], v[66:67], v[66:67]
	v_pk_mul_f32 v[78:79], v[34:35], v[34:35]
	v_pk_mul_f32 v[72:73], v[38:39], v[38:39]
	v_pk_mul_f32 v[74:75], v[36:37], v[36:37]
	global_load_dword v82, v[190:191], off offset:20
	global_load_dword v80, v[190:191], off offset:148
	global_load_dword v71, v[190:191], off offset:24
	global_load_dword v69, v[190:191], off offset:152
	v_mul_f32_e32 v6, v17, v146
	v_cvt_f64_f32_e32 v[6:7], v6
	v_mul_f64 v[8:9], v[6:7], s[82:83]
	v_rndne_f64_e32 v[8:9], v[8:9]
	v_fma_f64 v[6:7], v[6:7], s[82:83], -v[8:9]
	v_cvt_f32_f64_e32 v6, v[6:7]
	v_cos_f32_e32 v84, v6
	v_sin_f32_e32 v86, v6
	global_load_dword v10, v[196:197], off
	global_load_dword v83, v[194:195], off
	global_load_dword v81, v[194:195], off offset:128
	v_mul_f32_e32 v6, v18, v146
	v_cvt_f64_f32_e32 v[6:7], v6
	v_mul_f64 v[8:9], v[6:7], s[82:83]
	v_rndne_f64_e32 v[8:9], v[8:9]
	v_fma_f64 v[6:7], v[6:7], s[82:83], -v[8:9]
	v_cvt_f32_f64_e32 v6, v[6:7]
	v_cos_f32_e32 v17, v6
	v_sin_f32_e32 v33, v6
	s_waitcnt vmcnt(2)
	v_mul_f32_e32 v6, v10, v146
	v_cvt_f64_f32_e32 v[6:7], v6
	v_mul_f64 v[8:9], v[6:7], s[82:83]
	v_rndne_f64_e32 v[8:9], v[8:9]
	v_fma_f64 v[6:7], v[6:7], s[82:83], -v[8:9]
	v_cvt_f32_f64_e32 v6, v[6:7]
	v_cos_f32_e32 v85, v6
	v_sin_f32_e32 v87, v6
	global_load_dwordx4 v[6:9], v[192:193], off offset:80
	global_load_dwordx4 v[148:151], v[192:193], off offset:64
	global_load_dword v138, v[190:191], off offset:64
	global_load_dword v94, v[190:191], off offset:192
	v_lshlrev_b32_e32 v89, 16, v1
	v_lshlrev_b32_e32 v88, 16, v0
	v_and_b32_e32 v19, 0xffff0000, v1
	v_and_b32_e32 v18, 0xffff0000, v0
	v_lshlrev_b32_e32 v93, 16, v5
	v_lshlrev_b32_e32 v92, 16, v4
	v_and_b32_e32 v91, 0xffff0000, v5
	v_and_b32_e32 v90, 0xffff0000, v4
	v_pk_mul_f32 v[134:135], v[88:89], v[88:89]
	v_pk_mul_f32 v[136:137], v[18:19], v[18:19]
	v_pk_mul_f32 v[130:131], v[92:93], v[92:93]
	v_pk_mul_f32 v[132:133], v[90:91], v[90:91]
	s_waitcnt vmcnt(2)
	v_mul_f32_e32 v10, v148, v146
	v_cvt_f64_f32_e32 v[10:11], v10
	v_mul_f64 v[14:15], v[10:11], s[82:83]
	v_rndne_f64_e32 v[14:15], v[14:15]
	v_fma_f64 v[10:11], v[10:11], s[82:83], -v[14:15]
	v_cvt_f32_f64_e32 v11, v[10:11]
	v_cos_f32_e32 v10, v11
	v_sin_f32_e32 v14, v11
	global_load_dword v144, v[190:191], off offset:68
	global_load_dword v142, v[190:191], off offset:196
	global_load_dword v139, v[190:191], off offset:72
	global_load_dword v95, v[190:191], off offset:200
	v_mul_f32_e32 v0, v149, v146
	v_cvt_f64_f32_e32 v[0:1], v0
	v_mul_f64 v[4:5], v[0:1], s[82:83]
	v_rndne_f64_e32 v[4:5], v[4:5]
	v_fma_f64 v[0:1], v[0:1], s[82:83], -v[4:5]
	v_cvt_f32_f64_e32 v1, v[0:1]
	v_cos_f32_e32 v0, v1
	v_sin_f32_e32 v4, v1
	global_load_dword v145, v[190:191], off offset:76
	global_load_dword v143, v[190:191], off offset:204
	v_mul_f32_e32 v1, v150, v146
	v_cvt_f64_f32_e32 v[140:141], v1
	v_mul_f64 v[148:149], v[140:141], s[82:83]
	v_rndne_f64_e32 v[148:149], v[148:149]
	v_fma_f64 v[140:141], v[140:141], s[82:83], -v[148:149]
	v_cvt_f32_f64_e32 v1, v[140:141]
	v_cos_f32_e32 v11, v1
	v_sin_f32_e32 v15, v1
	v_mul_f32_e32 v1, v151, v146
	v_cvt_f64_f32_e32 v[140:141], v1
	v_mul_f64 v[148:149], v[140:141], s[82:83]
	v_rndne_f64_e32 v[148:149], v[148:149]
	v_fma_f64 v[140:141], v[140:141], s[82:83], -v[148:149]
	v_cvt_f32_f64_e32 v5, v[140:141]
	v_cos_f32_e32 v1, v5
	v_sin_f32_e32 v5, v5
	v_mul_f32_e32 v6, v6, v146
	v_cvt_f64_f32_e32 v[140:141], v6
	v_add_f32_e32 v6, v62, v64
	v_add_f32_e32 v6, v6, v63
	v_add_f32_e32 v6, v6, v65
	v_add_f32_e32 v6, v6, v76
	v_add_f32_e32 v6, v6, v78
	v_add_f32_e32 v6, v6, v77
	v_add_f32_e32 v6, v6, v79
	v_add_f32_e32 v6, v6, v134
	v_mul_f64 v[148:149], v[140:141], s[82:83]
	v_add_f32_e32 v6, v6, v136
	v_rndne_f64_e32 v[148:149], v[148:149]
	v_lshlrev_b32_e32 v151, 16, v3
	v_lshlrev_b32_e32 v150, 16, v2
	v_add_f32_e32 v6, v6, v135
	v_fma_f64 v[148:149], v[140:141], s[82:83], -v[148:149]
	v_pk_mul_f32 v[152:153], v[150:151], v[150:151]
	v_and_b32_e32 v141, 0xffff0000, v3
	v_and_b32_e32 v140, 0xffff0000, v2
	v_add_f32_e32 v6, v6, v137
	v_pk_mul_f32 v[2:3], v[140:141], v[140:141]
	v_add_f32_e32 v6, v6, v152
	v_add_f32_e32 v2, v6, v2
	v_add_f32_e32 v2, v2, v153
	v_add_f32_e32 v2, v2, v3
	v_add_f32_e32 v2, v2, v58
	v_add_f32_e32 v2, v2, v60
	v_add_f32_e32 v2, v2, v59
	v_add_f32_e32 v2, v2, v61
	v_add_f32_e32 v2, v2, v72
	v_add_f32_e32 v2, v2, v74
	v_add_f32_e32 v2, v2, v73
	v_add_f32_e32 v2, v2, v75
	v_add_f32_e32 v2, v2, v130
	v_add_f32_e32 v2, v2, v132
	v_add_f32_e32 v2, v2, v131
	v_add_f32_e32 v2, v2, v133
	v_fmac_f32_e32 v2, v24, v24
	v_fmac_f32_e32 v2, v20, v20
	v_add_f32_e32 v2, v2, v56
	v_add_f32_e32 v2, v2, v57
	v_mov_b32_e32 v3, v2
	s_nop 1
	v_permlane32_swap_b32_e32 v2, v3
	v_add_f32_e32 v2, v2, v3
	v_fmamk_f32 v2, v2, 0x3c800000, v253
	v_rsq_f32_e32 v3, v2
	v_cvt_f32_f64_e32 v6, v[148:149]
	v_cos_f32_e32 v2, v6
	v_sin_f32_e32 v6, v6
	v_mul_f32_e32 v56, 0x3d93cd3a, v3
	v_pk_mul_f32 v[44:45], v[56:57], v[44:45] op_sel_hi:[0,1]
	v_pk_mul_f32 v[44:45], v[54:55], v[44:45]
	global_load_dword v54, v[190:191], off offset:80
	global_load_dword v58, v[190:191], off offset:208
	v_pk_mul_f32 v[46:47], v[56:57], v[46:47] op_sel_hi:[0,1]
	v_pk_mul_f32 v[42:43], v[42:43], v[46:47]
	v_pk_mul_f32 v[46:47], v[56:57], v[48:49] op_sel_hi:[0,1]
	v_pk_mul_f32 v[40:41], v[40:41], v[46:47]
	v_pk_mul_f32 v[46:47], v[56:57], v[50:51] op_sel_hi:[0,1]
	v_pk_mul_f32 v[46:47], v[52:53], v[46:47]
	v_pk_mul_f32 v[48:49], v[42:43], v[26:27]
	v_pk_mul_f32 v[52:53], v[56:57], v[66:67] op_sel_hi:[0,1]
	v_pk_mul_f32 v[38:39], v[56:57], v[38:39] op_sel_hi:[0,1]
	v_pk_mul_f32 v[26:27], v[40:41], v[26:27]
	v_pk_fma_f32 v[48:49], v[40:41], v[12:13], v[48:49]
	v_pk_mul_f32 v[50:51], v[44:45], v[30:31]
	v_pk_mul_f32 v[52:53], v[70:71], v[52:53]
	v_pk_mul_f32 v[38:39], v[68:69], v[38:39]
	v_pk_mul_f32 v[36:37], v[56:57], v[36:37] op_sel_hi:[0,1]
	v_pk_fma_f32 v[12:13], v[42:43], v[12:13], v[26:27] neg_lo:[0,0,1] neg_hi:[0,0,1]
	v_pk_mul_f32 v[26:27], v[46:47], v[30:31]
	v_pk_fma_f32 v[50:51], v[46:47], v[28:29], v[50:51]
	v_pk_mul_f32 v[34:35], v[56:57], v[34:35] op_sel_hi:[0,1]
	v_pk_mul_f32 v[36:37], v[80:81], v[36:37]
	v_pk_mul_f32 v[60:61], v[52:53], v[32:33]
	v_pk_fma_f32 v[26:27], v[44:45], v[28:29], v[26:27] neg_lo:[0,0,1] neg_hi:[0,0,1]
	v_pk_mul_f32 v[28:29], v[38:39], v[32:33]
	v_pk_mul_f32 v[34:35], v[82:83], v[34:35]
	v_pk_fma_f32 v[60:61], v[38:39], v[16:17], v[60:61]
	v_pk_fma_f32 v[16:17], v[52:53], v[16:17], v[28:29] neg_lo:[0,0,1] neg_hi:[0,0,1]
	v_pk_mul_f32 v[28:29], v[36:37], v[86:87]
	v_bfe_u32 v25, v27, 16, 1
	v_pk_fma_f32 v[28:29], v[34:35], v[84:85], v[28:29] neg_lo:[0,0,1] neg_hi:[0,0,1]
	v_bfe_u32 v30, v26, 16, 1
	v_bfe_u32 v3, v29, 16, 1
	v_bfe_u32 v21, v28, 16, 1
	v_add3_u32 v21, v28, v21, s64
	v_add3_u32 v3, v29, v3, s64
	v_bfe_u32 v28, v13, 16, 1
	v_bfe_u32 v29, v16, 16, 1
	v_add3_u32 v25, v27, v25, s64
	v_bfe_u32 v27, v12, 16, 1
	v_add3_u32 v16, v16, v29, s64
	v_add3_u32 v13, v13, v28, s64
	v_pk_mul_f32 v[62:63], v[34:35], v[86:87]
	v_add3_u32 v26, v26, v30, s64
	v_bfe_u32 v30, v17, 16, 1
	v_add3_u32 v12, v12, v27, s64
	v_lshrrev_b32_e32 v13, 16, v13
	v_lshrrev_b32_e32 v16, 16, v16
	v_pk_fma_f32 v[62:63], v[36:37], v[84:85], v[62:63]
	v_add3_u32 v17, v17, v30, s64
	v_lshrrev_b32_e32 v12, 16, v12
	v_and_or_b32 v132, v21, s3, v16
	v_and_or_b32 v131, v25, s3, v13
	v_bfe_u32 v21, v49, 16, 1
	v_bfe_u32 v25, v60, 16, 1
	v_lshrrev_b32_e32 v17, 16, v17
	v_and_or_b32 v130, v26, s3, v12
	v_bfe_u32 v12, v62, 16, 1
	v_bfe_u32 v13, v51, 16, 1
	v_bfe_u32 v26, v61, 16, 1
	v_add3_u32 v25, v60, v25, s64
	v_add3_u32 v21, v49, v21, s64
	v_and_or_b32 v133, v3, s3, v17
	v_bfe_u32 v3, v63, 16, 1
	v_add3_u32 v13, v51, v13, s64
	v_add3_u32 v12, v62, v12, s64
	v_add3_u32 v26, v61, v26, s64
	v_lshrrev_b32_e32 v21, 16, v21
	v_lshrrev_b32_e32 v25, 16, v25
	v_add3_u32 v3, v63, v3, s64
	v_lshrrev_b32_e32 v26, 16, v26
	v_and_or_b32 v136, v12, s3, v25
	v_and_or_b32 v135, v13, s3, v21
	v_pk_mul_f32 v[12:13], v[56:57], v[88:89] op_sel_hi:[0,1]
	v_bfe_u32 v17, v48, 16, 1
	v_and_or_b32 v137, v3, s3, v26
	s_waitcnt vmcnt(5)
	v_pk_mul_f32 v[26:27], v[138:139], v[12:13]
	v_pk_mul_f32 v[12:13], v[56:57], v[92:93] op_sel_hi:[0,1]
	v_bfe_u32 v16, v50, 16, 1
	v_add3_u32 v17, v48, v17, s64
	s_waitcnt vmcnt(4)
	v_pk_mul_f32 v[28:29], v[94:95], v[12:13]
	v_pk_mul_f32 v[12:13], v[56:57], v[18:19] op_sel_hi:[0,1]
	v_add3_u32 v16, v50, v16, s64
	v_lshrrev_b32_e32 v17, 16, v17
	s_waitcnt vmcnt(3)
	v_pk_mul_f32 v[18:19], v[144:145], v[12:13]
	v_pk_mul_f32 v[12:13], v[56:57], v[90:91] op_sel_hi:[0,1]
	v_and_or_b32 v134, v16, s3, v17
	s_waitcnt vmcnt(2)
	v_pk_mul_f32 v[30:31], v[142:143], v[12:13]
	v_pk_mul_f32 v[12:13], v[26:27], v[14:15]
	v_pk_mul_f32 v[16:17], v[18:19], v[4:5]
	v_pk_fma_f32 v[12:13], v[28:29], v[10:11], v[12:13]
	v_pk_fma_f32 v[16:17], v[30:31], v[0:1], v[16:17]
	global_load_dword v32, v[190:191], off offset:84
	global_load_dword v34, v[190:191], off offset:212
	global_load_dword v55, v[190:191], off offset:88
	global_load_dword v59, v[190:191], off offset:216
	v_mul_f32_e32 v3, v7, v146
	v_cvt_f64_f32_e32 v[38:39], v3
	v_mul_f64 v[40:41], v[38:39], s[82:83]
	v_rndne_f64_e32 v[40:41], v[40:41]
	v_fma_f64 v[38:39], v[38:39], s[82:83], -v[40:41]
	v_cvt_f32_f64_e32 v3, v[38:39]
	v_mov_b32_e32 v25, v22
	v_cos_f32_e32 v22, v3
	v_sin_f32_e32 v38, v3
	v_pk_mul_f32 v[36:37], v[56:57], v[150:151] op_sel_hi:[0,1]
	v_pk_mul_f32 v[24:25], v[56:57], v[24:25] op_sel_hi:[0,1]
	s_waitcnt vmcnt(1)
	v_pk_mul_f32 v[36:37], v[54:55], v[36:37]
	s_waitcnt vmcnt(0)
	v_pk_mul_f32 v[24:25], v[58:59], v[24:25]
	global_load_dword v33, v[190:191], off offset:92
	global_load_dword v35, v[190:191], off offset:220
	v_mov_b32_e32 v21, v23
	v_pk_mul_f32 v[20:21], v[56:57], v[20:21] op_sel_hi:[0,1]
	v_mul_f32_e32 v3, v8, v146
	v_pk_mul_f32 v[40:41], v[56:57], v[140:141] op_sel_hi:[0,1]
	v_mul_f32_e32 v8, v9, v146
	v_cvt_f64_f32_e32 v[8:9], v8
	s_waitcnt vmcnt(1)
	v_pk_mul_f32 v[32:33], v[32:33], v[40:41]
	s_waitcnt vmcnt(0)
	v_pk_mul_f32 v[20:21], v[34:35], v[20:21]
	v_cvt_f64_f32_e32 v[34:35], v3
	v_mul_f64 v[40:41], v[34:35], s[82:83]
	v_rndne_f64_e32 v[40:41], v[40:41]
	v_fma_f64 v[34:35], v[34:35], s[82:83], -v[40:41]
	v_mul_f64 v[40:41], v[8:9], s[82:83]
	v_rndne_f64_e32 v[40:41], v[40:41]
	v_fma_f64 v[8:9], v[8:9], s[82:83], -v[40:41]
	v_cvt_f32_f64_e32 v7, v[34:35]
	v_cvt_f32_f64_e32 v8, v[8:9]
	v_cos_f32_e32 v3, v7
	v_sin_f32_e32 v7, v7
	v_sin_f32_e32 v39, v8
	v_cos_f32_e32 v23, v8
	v_pk_mul_f32 v[34:35], v[36:37], v[6:7]
	v_pk_mul_f32 v[8:9], v[32:33], v[38:39]
	v_pk_fma_f32 v[34:35], v[24:25], v[2:3], v[34:35]
	v_pk_fma_f32 v[8:9], v[20:21], v[22:23], v[8:9]
	v_pk_mul_f32 v[4:5], v[30:31], v[4:5]
	v_pk_mul_f32 v[14:15], v[28:29], v[14:15]
	v_pk_fma_f32 v[0:1], v[18:19], v[0:1], v[4:5] neg_lo:[0,0,1] neg_hi:[0,0,1]
	v_pk_mul_f32 v[4:5], v[24:25], v[6:7]
	v_pk_fma_f32 v[10:11], v[26:27], v[10:11], v[14:15] neg_lo:[0,0,1] neg_hi:[0,0,1]
	v_pk_fma_f32 v[2:3], v[36:37], v[2:3], v[4:5] neg_lo:[0,0,1] neg_hi:[0,0,1]
	v_pk_mul_f32 v[4:5], v[20:21], v[38:39]
	v_bfe_u32 v6, v1, 16, 1
	v_pk_fma_f32 v[4:5], v[32:33], v[22:23], v[4:5] neg_lo:[0,0,1] neg_hi:[0,0,1]
	v_bfe_u32 v7, v0, 16, 1
	v_bfe_u32 v14, v5, 16, 1
	v_bfe_u32 v15, v4, 16, 1
	v_add3_u32 v4, v4, v15, s64
	v_add3_u32 v5, v5, v14, s64
	v_bfe_u32 v14, v10, 16, 1
	v_bfe_u32 v15, v11, 16, 1
	v_add3_u32 v0, v0, v7, s64
	v_add3_u32 v1, v1, v6, s64
	v_bfe_u32 v6, v2, 16, 1
	v_bfe_u32 v7, v3, 16, 1
	v_add3_u32 v11, v11, v15, s64
	v_add3_u32 v10, v10, v14, s64
	v_add3_u32 v3, v3, v7, s64
	v_add3_u32 v2, v2, v6, s64
	v_lshrrev_b32_e32 v6, 16, v10
	v_lshrrev_b32_e32 v7, 16, v11
	v_lshrrev_b32_e32 v2, 16, v2
	v_lshrrev_b32_e32 v3, 16, v3
	v_and_or_b32 v139, v1, s3, v7
	v_and_or_b32 v138, v0, s3, v6
	v_bfe_u32 v6, v12, 16, 1
	v_bfe_u32 v7, v13, 16, 1
	v_and_or_b32 v141, v5, s3, v3
	v_and_or_b32 v140, v4, s3, v2
	v_bfe_u32 v0, v17, 16, 1
	v_bfe_u32 v1, v16, 16, 1
	v_bfe_u32 v4, v34, 16, 1
	v_bfe_u32 v5, v35, 16, 1
	v_add3_u32 v7, v13, v7, s64
	v_add3_u32 v6, v12, v6, s64
	v_bfe_u32 v2, v9, 16, 1
	v_bfe_u32 v3, v8, 16, 1
	v_add3_u32 v1, v16, v1, s64
	v_add3_u32 v0, v17, v0, s64
	v_add3_u32 v5, v35, v5, s64
	v_add3_u32 v4, v34, v4, s64
	v_lshrrev_b32_e32 v6, 16, v6
	v_lshrrev_b32_e32 v7, 16, v7
	v_add3_u32 v3, v8, v3, s64
	v_add3_u32 v2, v9, v2, s64
	v_lshrrev_b32_e32 v4, 16, v4
	v_lshrrev_b32_e32 v5, 16, v5
	v_and_or_b32 v143, v0, s3, v7
	v_and_or_b32 v142, v1, s3, v6
	s_lshr_b32 s55, s2, 6
	s_add_i32 s55, s55, 3
	s_cmp_lg_u64 s[30:31], 0
	s_cselect_b32 s55, s55, 0
	s_mul_i32 s56, s55, 0x30000
	s_add_u32 s36, s36, s56
	s_addc_u32 s37, s37, 0
	s_lshl_b32 s56, s55, 13
	s_add_u32 vcc_lo, vcc_lo, s56
	s_addc_u32 vcc_hi, vcc_hi, 0
	v_lshl_add_u64 v[0:1], v[176:177], 1, s[36:37]
	v_mov_b32_e32 v203, v97
	v_and_or_b32 v145, v2, s3, v5
	v_and_or_b32 v144, v3, s3, v4
	v_lshl_add_u64 v[8:9], v[0:1], 0, v[202:203]
	v_lshl_add_u64 v[4:5], v[178:179], 1, s[36:37]
	v_lshl_add_u64 v[16:17], vcc, 0, v[180:181]
	v_mov_b32_e32 v205, v97
	global_load_dwordx4 v[0:3], v[8:9], off offset:256
	v_lshl_add_u64 v[12:13], v[4:5], 0, v[202:203]
	v_lshl_add_u64 v[16:17], v[16:17], 0, v[204:205]
	global_load_dwordx4 v[4:7], v[12:13], off offset:256
	s_nop 0
	global_load_dwordx4 v[8:11], v[8:9], off
	s_nop 0
	global_load_dwordx4 v[12:15], v[12:13], off
	v_readfirstlane_b32 s55, v215
	global_load_dwordx4 v[16:19], v[16:17], off
	s_ashr_i32 s56, s55, 6
	s_cmp_gt_i32 s56, 3
	s_cselect_b64 s[80:81], -1, 0
	s_cmp_lt_i32 s56, 4
	s_cselect_b64 s[76:77], -1, 0
	s_and_b32 s55, s55, 0x3fffffc0
	s_lshl_b32 s55, s55, 2
	s_waitcnt vmcnt(0)
	s_lshr_b32 s63, s2, 6
	s_lshl_b32 s56, s56, 5
	s_add_i32 s69, s55, 0
	v_add_u32_e32 v20, 0, v216
	s_add_i32 s33, s63, 4
	s_add_i32 s2, s56, s2
	s_add_i32 s69, s69, 0x18000
	s_waitcnt vmcnt(4)
	ds_write_b128 v20, v[0:3]
	v_add_u32_e32 v0, 0, v217
	s_waitcnt vmcnt(3)
	ds_write_b128 v0, v[4:7]
	s_waitcnt vmcnt(2)
	ds_write_b128 v219, v[8:11] offset:49152
	s_waitcnt vmcnt(1)
	ds_write_b128 v219, v[12:15] offset:57344
	s_waitcnt vmcnt(0)
	ds_write_b128 v220, v[16:19]
	s_sub_u32 m0, s100, 0x2000
	s_add_u32 vcc_lo, vcc_lo, m0
	s_addc_u32 vcc_hi, vcc_hi, s101
	s_mul_i32 m0, m0, 24
	s_add_u32 s36, s36, m0
	s_addc_u32 s37, s37, s101
	v_lshl_add_u64 v[0:1], v[182:183], 1, s[36:37]
	v_lshl_add_u64 v[0:1], v[0:1], 0, v[202:203]
	v_lshl_add_u64 v[2:3], v[184:185], 1, s[36:37]
	v_lshl_add_u64 v[2:3], v[2:3], 0, v[202:203]
	global_load_dwordx4 v[146:149], v[0:1], off offset:256
	global_load_dwordx4 v[150:153], v[0:1], off
	global_load_dwordx4 v[154:157], v[2:3], off offset:256
	global_load_dwordx4 v[158:161], v[2:3], off
	v_lshl_add_u64 v[0:1], vcc, 0, v[186:187]
	v_lshl_add_u64 v[0:1], v[0:1], 0, v[204:205]
	global_load_dwordx4 v[162:165], v[0:1], off
	v_sub_u32_e32 v0, v168, v169
	v_add_u32_e32 v231, s2, v0
	v_lshl_add_u64 v[0:1], s[74:75], 0, v[198:199]
	v_lshl_add_u64 v[0:1], v[0:1], 0, s[20:21]
	s_mov_b64 s[36:37], 0x3e804000
	v_lshl_add_u64 v[206:207], v[0:1], 0, s[36:37]
	v_lshl_add_u64 v[0:1], s[42:43], 0, v[200:201]
	v_lshl_add_u64 v[0:1], v[0:1], 0, s[24:25]
	s_mov_b64 s[36:37], 0x32878100
	v_mov_b32_e32 v32, v97
	v_mov_b32_e32 v33, v97
	v_mov_b32_e32 v46, v97
	v_mov_b32_e32 v47, v97
	v_lshl_add_u64 v[208:209], v[0:1], 0, s[36:37]
	s_add_i32 m0, s33, -5
	s_cmp_lg_u64 s[30:31], 0
	s_cselect_b32 m0, m0, 0
	s_ashr_i32 s37, m0, 19
	s_lshl_b32 s36, m0, 13
	v_lshl_add_u64 v[206:207], v[206:207], 0, s[36:37]
	s_mul_i32 m0, m0, 3
	s_ashr_i32 s37, m0, 16
	s_lshl_b32 s36, m0, 16
	v_lshl_add_u64 v[208:209], v[208:209], 0, s[36:37]
	v_mov_b32_e32 v34, v97
	v_mov_b32_e32 v35, v97
	v_mov_b32_e32 v36, v97
	v_mov_b32_e32 v37, v97
	v_mov_b32_e32 v38, v97
	v_mov_b32_e32 v39, v97
	v_mov_b32_e32 v40, v97
	v_mov_b32_e32 v41, v97
	v_mov_b32_e32 v42, v97
	v_mov_b32_e32 v43, v97
	v_mov_b32_e32 v44, v97
	v_mov_b32_e32 v45, v97
	v_mov_b64_e32 v[62:63], v[46:47]
	v_mov_b64_e32 v[16:17], v[32:33]
	v_mov_b64_e32 v[0:1], v[32:33]
	s_add_i32 s55, s2, 0xfff0001f
	v_lshl_add_u32 v205, v168, 2, s69
	v_lshl_add_u32 v203, v169, 2, s69
	s_sub_i32 s63, -4, s63
	v_mov_b32_e32 v232, 0xf149f2ca
	v_mov_b32_e32 v233, 0
	v_mov_b32_e32 v64, 0
	v_mov_b32_e32 v65, 0
	v_mov_b32_e32 v66, 0
	v_mov_b32_e32 v67, 0
	v_mov_b32_e32 v68, 0
	v_mov_b32_e32 v69, 0
	v_mov_b32_e32 v70, 0
	v_mov_b32_e32 v71, 0
	v_mov_b32_e32 v72, 0
	v_mov_b32_e32 v73, 0
	v_mov_b32_e32 v74, 0
	v_mov_b32_e32 v75, 0
	v_mov_b32_e32 v76, 0
	v_mov_b32_e32 v77, 0
	v_mov_b32_e32 v78, 0
	v_mov_b32_e32 v79, 0
	s_add_i32 s8, s33, -1
	s_cmp_lg_u64 s[30:31], 0
	s_cselect_b32 s8, s8, 0
	s_lshl_b32 s8, s8, 6
	s_sub_i32 s69, 0, s8
	v_mov_b64_e32 v[60:61], v[44:45]
	v_mov_b64_e32 v[58:59], v[42:43]
	v_mov_b64_e32 v[56:57], v[40:41]
	v_mov_b64_e32 v[54:55], v[38:39]
	v_mov_b64_e32 v[52:53], v[36:37]
	v_mov_b64_e32 v[50:51], v[34:35]
	v_mov_b64_e32 v[48:49], v[32:33]
	v_mov_b64_e32 v[18:19], v[34:35]
	v_mov_b64_e32 v[20:21], v[36:37]
	v_mov_b64_e32 v[22:23], v[38:39]
	v_mov_b64_e32 v[24:25], v[40:41]
	v_mov_b64_e32 v[26:27], v[42:43]
	v_mov_b64_e32 v[28:29], v[44:45]
	v_mov_b64_e32 v[30:31], v[46:47]
	v_mov_b64_e32 v[2:3], v[34:35]
	v_mov_b64_e32 v[4:5], v[36:37]
	v_mov_b64_e32 v[6:7], v[38:39]
	v_mov_b64_e32 v[8:9], v[40:41]
	v_mov_b64_e32 v[10:11], v[42:43]
	v_mov_b64_e32 v[12:13], v[44:45]
	v_mov_b64_e32 v[14:15], v[46:47]
	s_mov_b32 s36, 0
	s_mov_b32 s37, 0
	s_waitcnt lgkmcnt(0)
	s_barrier
